# B-tile prefetch two rounds ahead at 64-byte stride (every sector touched)
# baseline (speedup 1.0000x reference)
.LBB0_372:
	s_add_u32 s8, s6, 0xfff80080
	s_addc_u32 s9, s7, -1
	s_add_i32 s21, 0, 0x10000
	v_add_u32_e32 v143, s21, v167
	ds_read_b128 v[148:151], v143
	ds_read_b128 v[152:155], v143 offset:1024
	ds_read_b128 v[156:159], v143 offset:2048
	ds_read_b128 v[160:163], v143 offset:3072
	s_cmp_eq_u32 s20, 28
	s_cselect_b32 s11, s17, s9
	s_cselect_b32 s10, s16, s8
	s_cselect_b32 s9, s19, s15
	s_cselect_b32 s8, s18, s13
	v_lshl_add_u64 v[164:165], s[6:7], 0, v[138:139]
	s_add_i32 m0, s40, 0xc000
	ds_read_b128 v[172:175], v171
	ds_read_b128 v[180:183], v171 offset:1024
	ds_read_b128 v[184:187], v171 offset:2048
	ds_read_b128 v[188:191], v171 offset:3072
	ds_read_b128 v[192:195], v171 offset:4096
	ds_read_b128 v[196:199], v171 offset:5120
	ds_read_b128 v[200:203], v171 offset:6144
	ds_read_b128 v[204:207], v171 offset:7168
	global_load_lds_dwordx4 v[164:165], off
	v_lshl_add_u64 v[164:165], s[6:7], 0, v[140:141]
	s_add_i32 m0, s40, 0xe000
	s_nop 0
	global_load_lds_dwordx4 v[164:165], off
	s_waitcnt lgkmcnt(8)
	s_barrier
	s_waitcnt lgkmcnt(0)
	s_setprio 1
	s_waitcnt lgkmcnt(0)
	v_mfma_f32_16x16x32_bf16 v[126:129], v[148:151], v[172:175], v[126:129]
	v_mfma_f32_16x16x32_bf16 v[122:125], v[156:159], v[172:175], v[122:125]
	v_mfma_f32_16x16x32_bf16 v[110:113], v[148:151], v[184:187], v[110:113]
	v_mfma_f32_16x16x32_bf16 v[106:109], v[156:159], v[184:187], v[106:109]
	v_mfma_f32_16x16x32_bf16 v[94:97], v[148:151], v[192:195], v[94:97]
	v_mfma_f32_16x16x32_bf16 v[90:93], v[156:159], v[192:195], v[90:93]
	v_mfma_f32_16x16x32_bf16 v[78:81], v[148:151], v[200:203], v[78:81]
	v_mfma_f32_16x16x32_bf16 v[74:77], v[156:159], v[200:203], v[74:77]
	v_mfma_f32_16x16x32_bf16 v[126:129], v[152:155], v[180:183], v[126:129]
	v_mfma_f32_16x16x32_bf16 v[122:125], v[160:163], v[180:183], v[122:125]
	v_mfma_f32_16x16x32_bf16 v[110:113], v[152:155], v[188:191], v[110:113]
	v_mfma_f32_16x16x32_bf16 v[106:109], v[160:163], v[188:191], v[106:109]
	v_mfma_f32_16x16x32_bf16 v[94:97], v[152:155], v[196:199], v[94:97]
	v_mfma_f32_16x16x32_bf16 v[90:93], v[160:163], v[196:199], v[90:93]
	v_mfma_f32_16x16x32_bf16 v[78:81], v[152:155], v[204:207], v[78:81]
	v_mfma_f32_16x16x32_bf16 v[74:77], v[160:163], v[204:207], v[74:77]
	s_setprio 0
	s_barrier
	s_add_i32 s24, 0, 0x14000
	s_add_i32 s21, s21, s39
	v_add_u32_e32 v143, s24, v167
	v_lshl_add_u64 v[164:165], s[8:9], 0, v[134:135]
	s_mov_b32 m0, s21
	ds_read_b128 v[208:211], v143
	ds_read_b128 v[212:215], v143 offset:1024
	ds_read_b128 v[216:219], v143 offset:2048
	ds_read_b128 v[220:223], v143 offset:3072
	global_load_lds_dwordx4 v[164:165], off
	v_lshl_add_u64 v[176:177], s[8:9], 0, v[130:131]
	s_add_i32 m0, s21, 0x2000
	s_nop 0
	global_load_lds_dwordx4 v[176:177], off
	s_barrier
	s_waitcnt lgkmcnt(0)
	s_setprio 1
	s_waitcnt lgkmcnt(0)
	v_mfma_f32_16x16x32_bf16 v[118:121], v[208:211], v[172:175], v[118:121]
	v_mfma_f32_16x16x32_bf16 v[114:117], v[216:219], v[172:175], v[114:117]
	v_mfma_f32_16x16x32_bf16 v[102:105], v[208:211], v[184:187], v[102:105]
	v_mfma_f32_16x16x32_bf16 v[98:101], v[216:219], v[184:187], v[98:101]
	v_mfma_f32_16x16x32_bf16 v[86:89], v[208:211], v[192:195], v[86:89]
	v_mfma_f32_16x16x32_bf16 v[82:85], v[216:219], v[192:195], v[82:85]
	v_mfma_f32_16x16x32_bf16 v[70:73], v[208:211], v[200:203], v[70:73]
	v_mfma_f32_16x16x32_bf16 v[66:69], v[216:219], v[200:203], v[66:69]
	v_mfma_f32_16x16x32_bf16 v[118:121], v[212:215], v[180:183], v[118:121]
	v_mfma_f32_16x16x32_bf16 v[114:117], v[220:223], v[180:183], v[114:117]
	v_mfma_f32_16x16x32_bf16 v[102:105], v[212:215], v[188:191], v[102:105]
	v_mfma_f32_16x16x32_bf16 v[98:101], v[220:223], v[188:191], v[98:101]
	v_mfma_f32_16x16x32_bf16 v[86:89], v[212:215], v[196:199], v[86:89]
	v_mfma_f32_16x16x32_bf16 v[82:85], v[220:223], v[196:199], v[82:85]
	v_mfma_f32_16x16x32_bf16 v[70:73], v[212:215], v[204:207], v[70:73]
	v_mfma_f32_16x16x32_bf16 v[66:69], v[220:223], v[204:207], v[66:69]
	s_setprio 0
	s_mov_b32 m0, s40
	v_lshl_add_u64 v[224:225], s[10:11], 0, v[136:137]
	s_barrier
	ds_read_b128 v[172:175], v171 offset:16384
	ds_read_b128 v[180:183], v171 offset:17408
	ds_read_b128 v[184:187], v171 offset:18432
	ds_read_b128 v[188:191], v171 offset:19456
	ds_read_b128 v[192:195], v171 offset:20480
	ds_read_b128 v[196:199], v171 offset:21504
	ds_read_b128 v[200:203], v171 offset:22528
	ds_read_b128 v[204:207], v171 offset:23552
	global_load_lds_dwordx4 v[224:225], off
	v_lshl_add_u64 v[236:237], s[10:11], 0, v[132:133]
	s_mov_b32 m0, s41
	s_nop 0
	global_load_lds_dwordx4 v[236:237], off
	s_barrier
	s_waitcnt lgkmcnt(0)
	s_setprio 1
	s_waitcnt lgkmcnt(0)
	v_mfma_f32_16x16x32_bf16 v[62:65], v[148:151], v[172:175], v[62:65]
	v_mfma_f32_16x16x32_bf16 v[58:61], v[156:159], v[172:175], v[58:61]
	v_mfma_f32_16x16x32_bf16 v[46:49], v[148:151], v[184:187], v[46:49]
	v_mfma_f32_16x16x32_bf16 v[42:45], v[156:159], v[184:187], v[42:45]
	v_mfma_f32_16x16x32_bf16 v[28:31], v[148:151], v[192:195], v[28:31]
	v_mfma_f32_16x16x32_bf16 v[24:27], v[156:159], v[192:195], v[24:27]
	v_mfma_f32_16x16x32_bf16 v[12:15], v[148:151], v[200:203], v[12:15]
	v_mfma_f32_16x16x32_bf16 v[8:11], v[156:159], v[200:203], v[8:11]
	v_mfma_f32_16x16x32_bf16 v[62:65], v[152:155], v[180:183], v[62:65]
	v_mfma_f32_16x16x32_bf16 v[58:61], v[160:163], v[180:183], v[58:61]
	v_mfma_f32_16x16x32_bf16 v[46:49], v[152:155], v[188:191], v[46:49]
	v_mfma_f32_16x16x32_bf16 v[42:45], v[160:163], v[188:191], v[42:45]
	v_mfma_f32_16x16x32_bf16 v[28:31], v[152:155], v[196:199], v[28:31]
	v_mfma_f32_16x16x32_bf16 v[24:27], v[160:163], v[196:199], v[24:27]
	v_mfma_f32_16x16x32_bf16 v[12:15], v[152:155], v[204:207], v[12:15]
	v_mfma_f32_16x16x32_bf16 v[8:11], v[160:163], v[204:207], v[8:11]
	s_setprio 0
	s_barrier
	s_add_u32 s22, s8, 0x80000
	s_addc_u32 s23, s9, 0
	s_add_i32 s21, s24, s39
	v_lshl_add_u64 v[148:149], s[22:23], 0, v[134:135]
	s_mov_b32 m0, s21
	s_nop 0
	global_load_lds_dwordx4 v[148:149], off
	v_lshl_add_u64 v[148:149], s[22:23], 0, v[130:131]
	s_add_i32 m0, s21, 0x2000
	s_nop 0
	global_load_lds_dwordx4 v[148:149], off
	s_waitcnt vmcnt(6)
	s_barrier
	s_setprio 1
	v_mfma_f32_16x16x32_bf16 v[54:57], v[208:211], v[172:175], v[54:57]
	v_mfma_f32_16x16x32_bf16 v[50:53], v[216:219], v[172:175], v[50:53]
	v_mfma_f32_16x16x32_bf16 v[38:41], v[208:211], v[184:187], v[38:41]
	v_mfma_f32_16x16x32_bf16 v[34:37], v[216:219], v[184:187], v[34:37]
	v_mfma_f32_16x16x32_bf16 v[20:23], v[208:211], v[192:195], v[20:23]
	v_mfma_f32_16x16x32_bf16 v[16:19], v[216:219], v[192:195], v[16:19]
	v_mfma_f32_16x16x32_bf16 v[4:7], v[208:211], v[200:203], v[4:7]
	v_mfma_f32_16x16x32_bf16 v[0:3], v[216:219], v[200:203], v[0:3]
	v_mfma_f32_16x16x32_bf16 v[54:57], v[212:215], v[180:183], v[54:57]
	v_mfma_f32_16x16x32_bf16 v[50:53], v[220:223], v[180:183], v[50:53]
	v_mfma_f32_16x16x32_bf16 v[38:41], v[212:215], v[188:191], v[38:41]
	v_mfma_f32_16x16x32_bf16 v[34:37], v[220:223], v[188:191], v[34:37]
	v_mfma_f32_16x16x32_bf16 v[20:23], v[212:215], v[196:199], v[20:23]
	v_mfma_f32_16x16x32_bf16 v[16:19], v[220:223], v[196:199], v[16:19]
	v_mfma_f32_16x16x32_bf16 v[4:7], v[212:215], v[204:207], v[4:7]
	v_mfma_f32_16x16x32_bf16 v[0:3], v[220:223], v[204:207], v[0:3]
	s_setprio 0
	s_add_i32 s21, 0, 0x18000
	v_add_u32_e32 v143, s21, v167
	s_barrier
	ds_read_b128 v[148:151], v143
	ds_read_b128 v[152:155], v143 offset:1024
	ds_read_b128 v[156:159], v143 offset:2048
	ds_read_b128 v[160:163], v143 offset:3072
	s_add_u32 s10, s10, 0x80000
	s_addc_u32 s11, s11, 0
	s_mov_b32 m0, s42
	v_lshl_add_u64 v[208:209], s[10:11], 0, v[136:137]
	ds_read_b128 v[172:175], v171 offset:32768
	ds_read_b128 v[180:183], v171 offset:33792
	ds_read_b128 v[184:187], v171 offset:34816
	ds_read_b128 v[188:191], v171 offset:35840
	ds_read_b128 v[192:195], v171 offset:36864
	ds_read_b128 v[196:199], v171 offset:37888
	ds_read_b128 v[200:203], v171 offset:38912
	ds_read_b128 v[204:207], v171 offset:39936
	global_load_lds_dwordx4 v[208:209], off
	v_lshl_add_u64 v[208:209], s[10:11], 0, v[132:133]
	s_mov_b32 m0, s43
	s_nop 0
	global_load_lds_dwordx4 v[208:209], off
	s_waitcnt lgkmcnt(8)
	s_barrier
	s_waitcnt lgkmcnt(0)
	s_setprio 1
	s_waitcnt lgkmcnt(0)
	v_mfma_f32_16x16x32_bf16 v[126:129], v[148:151], v[172:175], v[126:129]
	v_mfma_f32_16x16x32_bf16 v[122:125], v[156:159], v[172:175], v[122:125]
	v_mfma_f32_16x16x32_bf16 v[110:113], v[148:151], v[184:187], v[110:113]
	v_mfma_f32_16x16x32_bf16 v[106:109], v[156:159], v[184:187], v[106:109]
	v_mfma_f32_16x16x32_bf16 v[94:97], v[148:151], v[192:195], v[94:97]
	v_mfma_f32_16x16x32_bf16 v[90:93], v[156:159], v[192:195], v[90:93]
	v_mfma_f32_16x16x32_bf16 v[78:81], v[148:151], v[200:203], v[78:81]
	v_mfma_f32_16x16x32_bf16 v[74:77], v[156:159], v[200:203], v[74:77]
	v_mfma_f32_16x16x32_bf16 v[126:129], v[152:155], v[180:183], v[126:129]
	v_mfma_f32_16x16x32_bf16 v[122:125], v[160:163], v[180:183], v[122:125]
	v_mfma_f32_16x16x32_bf16 v[110:113], v[152:155], v[188:191], v[110:113]
	v_mfma_f32_16x16x32_bf16 v[106:109], v[160:163], v[188:191], v[106:109]
	v_mfma_f32_16x16x32_bf16 v[94:97], v[152:155], v[196:199], v[94:97]
	v_mfma_f32_16x16x32_bf16 v[90:93], v[160:163], v[196:199], v[90:93]
	v_mfma_f32_16x16x32_bf16 v[78:81], v[152:155], v[204:207], v[78:81]
	v_mfma_f32_16x16x32_bf16 v[74:77], v[160:163], v[204:207], v[74:77]
	s_setprio 0
	s_barrier
	s_add_i32 s10, 0, 0x1c000
	s_add_i32 s11, s21, s39
	v_add_u32_e32 v143, s10, v167
	v_lshl_add_u64 v[164:165], v[164:165], 0, s[88:89]
	s_mov_b32 m0, s11
	ds_read_b128 v[208:211], v143
	ds_read_b128 v[212:215], v143 offset:1024
	ds_read_b128 v[216:219], v143 offset:2048
	ds_read_b128 v[220:223], v143 offset:3072
	global_load_lds_dwordx4 v[164:165], off
	v_lshl_add_u64 v[164:165], v[176:177], 0, s[88:89]
	s_add_i32 m0, s11, 0x2000
	s_nop 0
	global_load_lds_dwordx4 v[164:165], off
	s_barrier
	s_waitcnt lgkmcnt(0)
	s_setprio 1
	s_waitcnt lgkmcnt(0)
	v_mfma_f32_16x16x32_bf16 v[118:121], v[208:211], v[172:175], v[118:121]
	v_mfma_f32_16x16x32_bf16 v[114:117], v[216:219], v[172:175], v[114:117]
	v_mfma_f32_16x16x32_bf16 v[102:105], v[208:211], v[184:187], v[102:105]
	v_mfma_f32_16x16x32_bf16 v[98:101], v[216:219], v[184:187], v[98:101]
	v_mfma_f32_16x16x32_bf16 v[86:89], v[208:211], v[192:195], v[86:89]
	v_mfma_f32_16x16x32_bf16 v[82:85], v[216:219], v[192:195], v[82:85]
	v_mfma_f32_16x16x32_bf16 v[70:73], v[208:211], v[200:203], v[70:73]
	v_mfma_f32_16x16x32_bf16 v[66:69], v[216:219], v[200:203], v[66:69]
	v_mfma_f32_16x16x32_bf16 v[118:121], v[212:215], v[180:183], v[118:121]
	v_mfma_f32_16x16x32_bf16 v[114:117], v[220:223], v[180:183], v[114:117]
	v_mfma_f32_16x16x32_bf16 v[102:105], v[212:215], v[188:191], v[102:105]
	v_mfma_f32_16x16x32_bf16 v[98:101], v[220:223], v[188:191], v[98:101]
	v_mfma_f32_16x16x32_bf16 v[86:89], v[212:215], v[196:199], v[86:89]
	v_mfma_f32_16x16x32_bf16 v[82:85], v[220:223], v[196:199], v[82:85]
	v_mfma_f32_16x16x32_bf16 v[70:73], v[212:215], v[204:207], v[70:73]
	v_mfma_f32_16x16x32_bf16 v[66:69], v[220:223], v[204:207], v[66:69]
	s_setprio 0
	s_mov_b32 m0, s46
	v_lshl_add_u64 v[164:165], v[224:225], 0, s[88:89]
	s_barrier
	ds_read_b128 v[172:175], v171 offset:49152
	ds_read_b128 v[180:183], v171 offset:50176
	ds_read_b128 v[184:187], v171 offset:51200
	ds_read_b128 v[188:191], v171 offset:52224
	ds_read_b128 v[192:195], v171 offset:53248
	ds_read_b128 v[196:199], v171 offset:54272
	ds_read_b128 v[200:203], v171 offset:55296
	ds_read_b128 v[204:207], v171 offset:56320
	global_load_lds_dwordx4 v[164:165], off
	v_lshl_add_u64 v[164:165], v[236:237], 0, s[88:89]
	s_mov_b32 m0, s47
	s_nop 0
	global_load_lds_dwordx4 v[164:165], off
	s_barrier
	s_waitcnt lgkmcnt(0)
	s_setprio 1
	s_waitcnt lgkmcnt(0)
	v_mfma_f32_16x16x32_bf16 v[62:65], v[148:151], v[172:175], v[62:65]
	v_mfma_f32_16x16x32_bf16 v[58:61], v[156:159], v[172:175], v[58:61]
	v_mfma_f32_16x16x32_bf16 v[46:49], v[148:151], v[184:187], v[46:49]
	v_mfma_f32_16x16x32_bf16 v[42:45], v[156:159], v[184:187], v[42:45]
	v_mfma_f32_16x16x32_bf16 v[28:31], v[148:151], v[192:195], v[28:31]
	v_mfma_f32_16x16x32_bf16 v[24:27], v[156:159], v[192:195], v[24:27]
	v_mfma_f32_16x16x32_bf16 v[12:15], v[148:151], v[200:203], v[12:15]
	v_mfma_f32_16x16x32_bf16 v[8:11], v[156:159], v[200:203], v[8:11]
	v_mfma_f32_16x16x32_bf16 v[62:65], v[152:155], v[180:183], v[62:65]
	v_mfma_f32_16x16x32_bf16 v[58:61], v[160:163], v[180:183], v[58:61]
	v_mfma_f32_16x16x32_bf16 v[46:49], v[152:155], v[188:191], v[46:49]
	v_mfma_f32_16x16x32_bf16 v[42:45], v[160:163], v[188:191], v[42:45]
	v_mfma_f32_16x16x32_bf16 v[28:31], v[152:155], v[196:199], v[28:31]
	v_mfma_f32_16x16x32_bf16 v[24:27], v[160:163], v[196:199], v[24:27]
	v_mfma_f32_16x16x32_bf16 v[12:15], v[152:155], v[204:207], v[12:15]
	v_mfma_f32_16x16x32_bf16 v[8:11], v[160:163], v[204:207], v[8:11]
	s_setprio 0
	s_barrier
	s_add_u32 s8, s8, 0x80080
	s_addc_u32 s9, s9, 0
	s_add_i32 s10, s10, s39
	v_lshl_add_u64 v[148:149], s[8:9], 0, v[134:135]
	s_mov_b32 m0, s10
	s_nop 0
	global_load_lds_dwordx4 v[148:149], off
	v_lshl_add_u64 v[148:149], s[8:9], 0, v[130:131]
	s_add_i32 m0, s10, 0x2000
	s_nop 0
	global_load_lds_dwordx4 v[148:149], off
	s_waitcnt vmcnt(6)
	s_barrier
	s_setprio 1
	v_mfma_f32_16x16x32_bf16 v[54:57], v[208:211], v[172:175], v[54:57]
	v_mfma_f32_16x16x32_bf16 v[50:53], v[216:219], v[172:175], v[50:53]
	v_mfma_f32_16x16x32_bf16 v[38:41], v[208:211], v[184:187], v[38:41]
	v_mfma_f32_16x16x32_bf16 v[34:37], v[216:219], v[184:187], v[34:37]
	v_mfma_f32_16x16x32_bf16 v[20:23], v[208:211], v[192:195], v[20:23]
	v_mfma_f32_16x16x32_bf16 v[16:19], v[216:219], v[192:195], v[16:19]
	v_mfma_f32_16x16x32_bf16 v[4:7], v[208:211], v[200:203], v[4:7]
	v_mfma_f32_16x16x32_bf16 v[0:3], v[216:219], v[200:203], v[0:3]
	v_mfma_f32_16x16x32_bf16 v[54:57], v[212:215], v[180:183], v[54:57]
	v_mfma_f32_16x16x32_bf16 v[50:53], v[220:223], v[180:183], v[50:53]
	v_mfma_f32_16x16x32_bf16 v[38:41], v[212:215], v[188:191], v[38:41]
	v_mfma_f32_16x16x32_bf16 v[34:37], v[220:223], v[188:191], v[34:37]
	v_mfma_f32_16x16x32_bf16 v[20:23], v[212:215], v[196:199], v[20:23]
	v_mfma_f32_16x16x32_bf16 v[16:19], v[220:223], v[196:199], v[16:19]
	v_mfma_f32_16x16x32_bf16 v[4:7], v[212:215], v[204:207], v[4:7]
	v_mfma_f32_16x16x32_bf16 v[0:3], v[220:223], v[204:207], v[0:3]
	s_setprio 0
	s_add_i32 s20, s20, 2
	s_add_u32 s6, s6, 0x100
	s_addc_u32 s7, s7, 0
	s_add_u32 s13, s13, 0x100
	s_addc_u32 s15, s15, 0
	s_cmp_gt_u32 s20, 29
	s_barrier
	s_cbranch_scc0 .LBB0_372
	s_sub_i32 s6, s51, 8
	s_cmp_lt_u32 s6, 8
	s_cbranch_scc1 .Lmain_old
	s_sub_i32 s6, s51, 32
	s_cmp_lt_u32 s6, 12
	s_cbranch_scc1 .Lmain_kv
	v_mbcnt_lo_u32_b32 v217, -1, 0
	v_mbcnt_hi_u32_b32 v217, -1, v217
	s_add_i32 s24, s51, 8
	s_cmp_lt_u32 s24, 92
	s_cbranch_scc0 .Lmain_nopf
	s_lshl_b32 s24, s24, 20
	s_and_b32 s25, s33, 63
	s_lshl_b32 s25, s25, 14
	s_add_i32 s24, s24, s25
	s_add_u32 s24, s48, s24
	s_addc_u32 s25, s49, 0
	v_lshlrev_b32_e32 v218, 6, v217
	global_load_dword v219, v218, s[24:25]
	s_add_u32 s24, s24, 0x1000
	s_addc_u32 s25, s25, 0
	global_load_dword v219, v218, s[24:25]
	s_add_u32 s24, s24, 0x1000
	s_addc_u32 s25, s25, 0
	global_load_dword v219, v218, s[24:25]
	s_add_u32 s24, s24, 0x1000
	s_addc_u32 s25, s25, 0
	global_load_dword v219, v218, s[24:25]
